# plus: FFN-up epilogue canonicalize+relu fused; P0 weight-transpose tile loads batched (one wait per tile), MLA dead zero-inits removed
# speedup vs baseline: 1.0189x; 1.0001x over previous
; template <int MODE>
; DEVI void attn_item(const Params& p, int item, unsigned char* smem) {
;     ...
;       f32x16 SA[NH][2]; bool relq[NH];
; #pragma unroll
;       for (int hfi = 0; hfi < NH; ++hfi) {
;         const int hf = NH - 1 - hfi, kt = kT * NH + hf;
;         unsigned char* Ks = smem + hf * 64 * C::KSTR;
;         bool rel = wactive && (kt <= kt_last);
;         if constexpr (MODE == 0) rel = rel && !done && (samp || kt * 64 < wave_qmax);
;         if constexpr (MODE == 1) rel = rel && (kt <= wave_chunk);
;         relq[hf] = rel;
;         SA[hf][0] = (f32x16){}; SA[hf][1] = (f32x16){};
;         if (rel) {
;                 constexpr int CH = (KS % 6 == 0) ? 6 : 4;
; #pragma unroll
;                 for (int c0 = 0; c0 < KS; c0 += CH) {
;                     bf16x8 ka[2][CH], qb[CH];
; #pragma unroll
;                     for (int s = 0; s < CH; ++s) {
;                         ka[0][s] = *(const bf16x8*)(Ks + (r) * C::KSTR + ((c0 + s) * 16 + 8 * h) * 2);
;                         ka[1][s] = *(const bf16x8*)(Ks + (32 + r) * C::KSTR + ((c0 + s) * 16 + 8 * h) * 2);
;                         if constexpr (MODE == 2) qb[s] = *(const bf16x8*)(Qs + (rg * 32 + r) * 592 + ((c0 + s) * 16 + 8 * h) * 2); else qb[s] = qf[c0 + s];
;                     }
;                     __builtin_amdgcn_sched_barrier(0);
; #pragma unroll
;                     for (int s = 0; s < CH; ++s) {
;                         SA[hf][0] = __builtin_amdgcn_mfma_f32_32x32x16_bf16(ka[0][s], qb[s], SA[hf][0], 0, 0, 0);
;                         SA[hf][1] = __builtin_amdgcn_mfma_f32_32x32x16_bf16(ka[1][s], qb[s], SA[hf][1], 0, 0, 0);
;                     }
;                 }
;         }
.LBB0_257:
	v_cmp_lt_i32_e64 s[46:47], s8, v188
	s_nop 3
	s_and_saveexec_b64 s[0:1], s[46:47]
	s_cbranch_execz .LBB0_259
	ds_read_b128 v[38:41], v196 offset:13312
	ds_read_b128 v[42:45], v196 offset:13344
	ds_read_b128 v[46:49], v196 offset:19968
	ds_read_b128 v[50:53], v196 offset:20000
	ds_read_b128 v[54:57], v196 offset:13376
	ds_read_b128 v[58:61], v196 offset:13408
	ds_read_b128 v[62:65], v196 offset:20032
	ds_read_b128 v[168:171], v196 offset:20064
	ds_read_b128 v[176:179], v196 offset:13440
	ds_read_b128 v[182:185], v196 offset:13472
	ds_read_b128 v[200:203], v196 offset:20096
	ds_read_b128 v[204:207], v196 offset:20128
	s_waitcnt lgkmcnt(11)
	v_mfma_f32_32x32x16_bf16 v[84:99], v[38:41], v[100:103], 0
	s_waitcnt lgkmcnt(9)
	v_mfma_f32_32x32x16_bf16 v[68:83], v[46:49], v[100:103], 0
	v_mfma_f32_32x32x16_bf16 v[84:99], v[42:45], v[104:107], v[84:99]
	s_waitcnt lgkmcnt(8)
	v_mfma_f32_32x32x16_bf16 v[68:83], v[50:53], v[104:107], v[68:83]
	s_waitcnt lgkmcnt(7)
	v_mfma_f32_32x32x16_bf16 v[84:99], v[54:57], v[108:111], v[84:99]
	s_waitcnt lgkmcnt(5)
	v_mfma_f32_32x32x16_bf16 v[68:83], v[62:65], v[108:111], v[68:83]
	v_mfma_f32_32x32x16_bf16 v[84:99], v[58:61], v[112:115], v[84:99]
	s_waitcnt lgkmcnt(4)
	v_mfma_f32_32x32x16_bf16 v[68:83], v[168:171], v[112:115], v[68:83]
	s_waitcnt lgkmcnt(3)
	v_mfma_f32_32x32x16_bf16 v[84:99], v[176:179], v[140:143], v[84:99]
	s_waitcnt lgkmcnt(1)
	v_mfma_f32_32x32x16_bf16 v[68:83], v[200:203], v[140:143], v[68:83]
	v_mfma_f32_32x32x16_bf16 v[84:99], v[182:185], v[136:139], v[84:99]
	s_waitcnt lgkmcnt(0)
	v_mfma_f32_32x32x16_bf16 v[68:83], v[204:207], v[136:139], v[68:83]
.LBB0_259:
	s_or_b64 exec, exec, s[0:1]
	v_cmp_le_i32_e64 s[44:45], s8, v188
	s_nop 3
	s_and_saveexec_b64 s[0:1], s[44:45]
	s_cbranch_execz .LBB0_262
	ds_read_b128 v[36:39], v196
	ds_read_b128 v[168:171], v196 offset:32
	ds_read_b128 v[40:43], v196 offset:6656
	ds_read_b128 v[176:179], v196 offset:6688
	ds_read_b128 v[182:185], v196 offset:64
	ds_read_b128 v[200:203], v196 offset:96
	ds_read_b128 v[204:207], v196 offset:6720
	ds_read_b128 v[208:211], v196 offset:6752
	ds_read_b128 v[212:215], v196 offset:128
	ds_read_b128 v[216:219], v196 offset:160
	ds_read_b128 v[220:223], v196 offset:6784
	ds_read_b128 v[224:227], v196 offset:6816
	s_waitcnt lgkmcnt(11)
	v_mfma_f32_32x32x16_bf16 v[52:67], v[36:39], v[100:103], 0
	s_waitcnt lgkmcnt(9)
	v_mfma_f32_32x32x16_bf16 v[36:51], v[40:43], v[100:103], 0
	v_mfma_f32_32x32x16_bf16 v[52:67], v[168:171], v[104:107], v[52:67]
	s_waitcnt lgkmcnt(8)
	v_mfma_f32_32x32x16_bf16 v[36:51], v[176:179], v[104:107], v[36:51]
	s_waitcnt lgkmcnt(7)
	v_mfma_f32_32x32x16_bf16 v[52:67], v[182:185], v[108:111], v[52:67]
	s_waitcnt lgkmcnt(5)
	v_mfma_f32_32x32x16_bf16 v[36:51], v[204:207], v[108:111], v[36:51]
	v_mfma_f32_32x32x16_bf16 v[52:67], v[200:203], v[112:115], v[52:67]
	s_waitcnt lgkmcnt(4)
	v_mfma_f32_32x32x16_bf16 v[36:51], v[208:211], v[112:115], v[36:51]
	s_waitcnt lgkmcnt(3)
	v_mfma_f32_32x32x16_bf16 v[52:67], v[212:215], v[140:143], v[52:67]
	s_waitcnt lgkmcnt(1)
	v_mfma_f32_32x32x16_bf16 v[36:51], v[220:223], v[140:143], v[36:51]
	v_mfma_f32_32x32x16_bf16 v[52:67], v[216:219], v[136:139], v[52:67]
	s_waitcnt lgkmcnt(0)
	v_mfma_f32_32x32x16_bf16 v[36:51], v[224:227], v[136:139], v[36:51]
	s_or_b64 exec, exec, s[0:1]
	s_and_saveexec_b64 s[70:71], s[46:47]
	s_cbranch_execnz .LBB0_263

; DEVI void st_bf16x8(bf16_t* p, f32x4 a, f32x4 b) { u32x4 w; w.x = pk2(a[0], a[1]); w.y = pk2(a[2], a[3]); w.z = pk2(b[0], b[1]); w.w = pk2(b[2], b[3]); *(u32x4*)p = w; }
; template <int NSTORE, class TF, class F>
; DEVI void gemm_run(const bf16_t* __restrict__ A, int lda, const bf16_t* __restrict__ Bt, int ldb, int K, bf16_t* shm, TF&& tile, F&& emit) {
;     ...
;         for (int ai = 0; ai < 2; ++ai)
; #pragma unroll
;             for (int m = 0; m < 4; ++m)
; #pragma unroll
;                 for (int bj = 0; bj < 2; ++bj)
;                     emit(brow + ai * HALF + wr * 64 + m * 16 + fr, bcol + bj * HALF + wc * 32 + fq * 8, acc[ai][bj][m][0], acc[ai][bj][m][1]);
; __global__ void __launch_bounds__(512) mega(Params p, int ph_lo, int ph_hi, int coop) {
;     ...
;             auto emit = [&](int row, int col, f32x4 v0, f32x4 v1) {
; #pragma unroll
;                 for (int k = 0; k < 4; ++k) { float a = fmaxf(v0[k], 0.f), b2 = fmaxf(v1[k], 0.f); v0[k] = a * a; v1[k] = b2 * b2; }
;                 bf16_t* d = ACT + (size_t)row * 4096 + col; st_bf16x8(d, v0, v1);
;             };
.LBB0_515:
	v_add_u32_e32 v140, s26, v142
	v_max_f32_e32 v122, 0, v122
	v_ashrrev_i32_e32 v141, 31, v140
	v_lshlrev_b64 v[148:149], 13, v[140:141]
	v_mul_f32_e32 v141, v122, v122
	v_max_f32_e32 v122, 0, v127
	v_max_f32_e32 v123, 0, v123
	v_mul_f32_e32 v127, v122, v122
	v_mul_f32_e32 v150, v123, v123
	v_max_f32_e32 v122, 0, v128
	v_max_f32_e32 v123, 0, v124
	v_add_u32_e32 v146, s27, v145
	v_max_f32_e32 v126, 0, v126
	v_mul_f32_e32 v151, v122, v122
	v_mul_f32_e32 v152, v123, v123
	v_max_f32_e32 v122, 0, v129
	v_max_f32_e32 v123, 0, v125
	v_ashrrev_i32_e32 v147, 31, v146
	v_mul_f32_e32 v126, v126, v126
	v_mul_f32_e32 v153, v122, v122
	v_mul_f32_e32 v154, v123, v123
	v_lshl_add_u64 v[124:125], s[22:23], 0, v[148:149]
	v_lshlrev_b64 v[122:123], 1, v[146:147]
	v_max_f32_e32 v114, 0, v114
	v_max_f32_e32 v115, 0, v115
	v_max_f32_e32 v116, 0, v116
	v_lshl_add_u64 v[128:129], v[124:125], 0, v[122:123]
	v_cvt_pk_bf16_f32 v124, v126, v127
	v_cvt_pk_bf16_f32 v125, v151, v153
	v_cvt_pk_bf16_f32 v126, v141, v150
	v_cvt_pk_bf16_f32 v127, v152, v154
	global_store_dwordx4 v[128:129], v[124:127], off
	s_nop 1
	v_max_f32_e32 v118, 0, v118
	v_max_f32_e32 v117, 0, v117
	v_mul_f32_e32 v124, v114, v114
	v_max_f32_e32 v114, 0, v119
	v_mul_f32_e32 v119, v115, v115
	v_max_f32_e32 v115, 0, v120
	v_mul_f32_e32 v120, v116, v116
	v_max_f32_e32 v116, 0, v121
	v_mul_f32_e32 v118, v118, v118
	v_mul_f32_e32 v114, v114, v114
	v_mul_f32_e32 v115, v115, v115
	v_mul_f32_e32 v116, v116, v116
	v_mul_f32_e32 v117, v117, v117
	v_max_f32_e32 v106, 0, v106
	v_cvt_pk_bf16_f32 v114, v118, v114
	v_cvt_pk_bf16_f32 v115, v115, v116
	v_cvt_pk_bf16_f32 v116, v124, v119
	v_cvt_pk_bf16_f32 v117, v120, v117
	global_store_dwordx4 v[128:129], v[114:117], off offset:256
	s_nop 1
	v_max_f32_e32 v107, 0, v107
	v_mul_f32_e32 v117, v106, v106
	v_max_f32_e32 v106, 0, v111
	v_mul_f32_e32 v118, v106, v106
	v_mul_f32_e32 v119, v107, v107
	v_max_f32_e32 v106, 0, v112
	v_max_f32_e32 v107, 0, v108
	v_add_u32_e32 v114, 16, v140
	v_ashrrev_i32_e32 v115, 31, v114
	v_max_f32_e32 v110, 0, v110
	v_mul_f32_e32 v108, v106, v106
	v_mul_f32_e32 v112, v107, v107
	v_max_f32_e32 v106, 0, v113
	v_max_f32_e32 v107, 0, v109
	v_lshlrev_b64 v[114:115], 13, v[114:115]
	v_mul_f32_e32 v116, v110, v110
	v_mul_f32_e32 v109, v106, v106
	v_mul_f32_e32 v113, v107, v107
	v_lshl_add_u64 v[106:107], s[22:23], 0, v[114:115]
	v_max_f32_e32 v98, 0, v98
	v_max_f32_e32 v99, 0, v99
	v_max_f32_e32 v100, 0, v100
	v_lshl_add_u64 v[110:111], v[106:107], 0, v[122:123]
	v_cvt_pk_bf16_f32 v106, v116, v118
	v_cvt_pk_bf16_f32 v107, v108, v109
	v_cvt_pk_bf16_f32 v108, v117, v119
	v_cvt_pk_bf16_f32 v109, v112, v113
	global_store_dwordx4 v[110:111], v[106:109], off
	s_nop 1
	v_max_f32_e32 v102, 0, v102
	v_max_f32_e32 v101, 0, v101
	v_mul_f32_e32 v106, v98, v98
	v_max_f32_e32 v98, 0, v103
	v_mul_f32_e32 v103, v99, v99
	v_max_f32_e32 v99, 0, v104
	v_mul_f32_e32 v104, v100, v100
	v_max_f32_e32 v100, 0, v105
	v_mul_f32_e32 v102, v102, v102
	v_mul_f32_e32 v98, v98, v98
	v_mul_f32_e32 v99, v99, v99
	v_mul_f32_e32 v100, v100, v100
	v_mul_f32_e32 v101, v101, v101
	v_max_f32_e32 v90, 0, v90
	v_cvt_pk_bf16_f32 v98, v102, v98
	v_cvt_pk_bf16_f32 v99, v99, v100
	v_cvt_pk_bf16_f32 v100, v106, v103
	v_cvt_pk_bf16_f32 v101, v104, v101
	global_store_dwordx4 v[110:111], v[98:101], off offset:256
	s_nop 1
	v_max_f32_e32 v91, 0, v91
	v_mul_f32_e32 v101, v90, v90
	v_max_f32_e32 v90, 0, v95
	v_mul_f32_e32 v102, v90, v90
	v_mul_f32_e32 v103, v91, v91
	v_max_f32_e32 v90, 0, v96
	v_max_f32_e32 v91, 0, v92
	v_add_u32_e32 v98, 32, v140
	v_ashrrev_i32_e32 v99, 31, v98
	v_max_f32_e32 v94, 0, v94
	v_mul_f32_e32 v92, v90, v90
	v_mul_f32_e32 v96, v91, v91
	v_max_f32_e32 v90, 0, v97
	v_max_f32_e32 v91, 0, v93
	v_lshlrev_b64 v[98:99], 13, v[98:99]
	v_mul_f32_e32 v100, v94, v94
	v_mul_f32_e32 v93, v90, v90
	v_mul_f32_e32 v97, v91, v91
	v_lshl_add_u64 v[90:91], s[22:23], 0, v[98:99]
	v_max_f32_e32 v82, 0, v82
	v_max_f32_e32 v83, 0, v83
	v_max_f32_e32 v84, 0, v84
	v_lshl_add_u64 v[94:95], v[90:91], 0, v[122:123]
	v_cvt_pk_bf16_f32 v90, v100, v102
	v_cvt_pk_bf16_f32 v91, v92, v93
	v_cvt_pk_bf16_f32 v92, v101, v103
	v_cvt_pk_bf16_f32 v93, v96, v97
	global_store_dwordx4 v[94:95], v[90:93], off
	s_nop 1
	v_max_f32_e32 v86, 0, v86
	v_max_f32_e32 v85, 0, v85
	v_mul_f32_e32 v90, v82, v82
	v_max_f32_e32 v82, 0, v87
	v_mul_f32_e32 v87, v83, v83
	v_max_f32_e32 v83, 0, v88
	v_mul_f32_e32 v88, v84, v84
	v_max_f32_e32 v84, 0, v89
	v_mul_f32_e32 v86, v86, v86
	v_mul_f32_e32 v82, v82, v82
	v_mul_f32_e32 v83, v83, v83
	v_mul_f32_e32 v84, v84, v84
	v_mul_f32_e32 v85, v85, v85
	v_max_f32_e32 v74, 0, v74
	v_cvt_pk_bf16_f32 v82, v86, v82
	v_cvt_pk_bf16_f32 v83, v83, v84
	v_cvt_pk_bf16_f32 v84, v90, v87
	v_cvt_pk_bf16_f32 v85, v88, v85
	global_store_dwordx4 v[94:95], v[82:85], off offset:256
	s_nop 1
	v_max_f32_e32 v75, 0, v75
	v_mul_f32_e32 v85, v74, v74
	v_max_f32_e32 v74, 0, v79
	v_mul_f32_e32 v86, v74, v74
	v_mul_f32_e32 v87, v75, v75
	v_max_f32_e32 v74, 0, v80
	v_max_f32_e32 v75, 0, v76
	v_add_u32_e32 v82, 48, v140
	v_ashrrev_i32_e32 v83, 31, v82
	v_max_f32_e32 v78, 0, v78
	v_mul_f32_e32 v76, v74, v74
	v_mul_f32_e32 v80, v75, v75
	v_max_f32_e32 v74, 0, v81
	v_max_f32_e32 v75, 0, v77
	v_lshlrev_b64 v[82:83], 13, v[82:83]
	v_mul_f32_e32 v84, v78, v78
	v_mul_f32_e32 v77, v74, v74
	v_mul_f32_e32 v81, v75, v75
	v_lshl_add_u64 v[74:75], s[22:23], 0, v[82:83]
	v_max_f32_e32 v66, 0, v66
	v_max_f32_e32 v67, 0, v67
	v_max_f32_e32 v68, 0, v68
	v_lshl_add_u64 v[78:79], v[74:75], 0, v[122:123]
	v_cvt_pk_bf16_f32 v74, v84, v86
	v_cvt_pk_bf16_f32 v75, v76, v77
	v_cvt_pk_bf16_f32 v76, v85, v87
	v_cvt_pk_bf16_f32 v77, v80, v81
; DEVI void st_bf16x8(bf16_t* p, f32x4 a, f32x4 b) { u32x4 w; w.x = pk2(a[0], a[1]); w.y = pk2(a[2], a[3]); w.z = pk2(b[0], b[1]); w.w = pk2(b[2], b[3]); *(u32x4*)p = w; }
; template <int NSTORE, class TF, class F>
; DEVI void gemm_run(const bf16_t* __restrict__ A, int lda, const bf16_t* __restrict__ Bt, int ldb, int K, bf16_t* shm, TF&& tile, F&& emit) {
;     ...
;         for (int ai = 0; ai < 2; ++ai)
; #pragma unroll
;             for (int m = 0; m < 4; ++m)
; #pragma unroll
;                 for (int bj = 0; bj < 2; ++bj)
;                     emit(brow + ai * HALF + wr * 64 + m * 16 + fr, bcol + bj * HALF + wc * 32 + fq * 8, acc[ai][bj][m][0], acc[ai][bj][m][1]);
; __global__ void __launch_bounds__(512) mega(Params p, int ph_lo, int ph_hi, int coop) {
;     ...
;             auto emit = [&](int row, int col, f32x4 v0, f32x4 v1) {
; #pragma unroll
;                 for (int k = 0; k < 4; ++k) { float a = fmaxf(v0[k], 0.f), b2 = fmaxf(v1[k], 0.f); v0[k] = a * a; v1[k] = b2 * b2; }
;                 bf16_t* d = ACT + (size_t)row * 4096 + col; st_bf16x8(d, v0, v1);
;             };
	global_store_dwordx4 v[78:79], v[74:77], off
	s_nop 1
	v_max_f32_e32 v70, 0, v70
	v_max_f32_e32 v69, 0, v69
	v_mul_f32_e32 v74, v66, v66
	v_max_f32_e32 v66, 0, v71
	v_mul_f32_e32 v71, v67, v67
	v_max_f32_e32 v67, 0, v72
	v_mul_f32_e32 v72, v68, v68
	v_max_f32_e32 v68, 0, v73
	v_mul_f32_e32 v70, v70, v70
	v_mul_f32_e32 v66, v66, v66
	v_mul_f32_e32 v67, v67, v67
	v_mul_f32_e32 v68, v68, v68
	v_mul_f32_e32 v69, v69, v69
	v_max_f32_e32 v58, 0, v58
	v_cvt_pk_bf16_f32 v66, v70, v66
	v_cvt_pk_bf16_f32 v67, v67, v68
	v_cvt_pk_bf16_f32 v68, v74, v71
	v_cvt_pk_bf16_f32 v69, v72, v69
	global_store_dwordx4 v[78:79], v[66:69], off offset:256
	s_nop 1
	v_max_f32_e32 v59, 0, v59
	v_mul_f32_e32 v69, v58, v58
	v_max_f32_e32 v58, 0, v63
	v_mul_f32_e32 v70, v58, v58
	v_mul_f32_e32 v71, v59, v59
	v_max_f32_e32 v58, 0, v64
	v_max_f32_e32 v59, 0, v60
	v_add_u32_e32 v66, 0x80, v140
	v_ashrrev_i32_e32 v67, 31, v66
	v_max_f32_e32 v62, 0, v62
	v_mul_f32_e32 v60, v58, v58
	v_mul_f32_e32 v64, v59, v59
	v_max_f32_e32 v58, 0, v65
	v_max_f32_e32 v59, 0, v61
	v_lshlrev_b64 v[66:67], 13, v[66:67]
	v_mul_f32_e32 v68, v62, v62
	v_mul_f32_e32 v61, v58, v58
	v_mul_f32_e32 v65, v59, v59
	v_lshl_add_u64 v[58:59], s[22:23], 0, v[66:67]
	v_max_f32_e32 v50, 0, v50
	v_max_f32_e32 v51, 0, v51
	v_max_f32_e32 v52, 0, v52
	v_lshl_add_u64 v[62:63], v[58:59], 0, v[122:123]
	v_cvt_pk_bf16_f32 v58, v68, v70
	v_cvt_pk_bf16_f32 v59, v60, v61
	v_cvt_pk_bf16_f32 v60, v69, v71
	v_cvt_pk_bf16_f32 v61, v64, v65
	global_store_dwordx4 v[62:63], v[58:61], off
	s_nop 1
	v_max_f32_e32 v54, 0, v54
	v_max_f32_e32 v53, 0, v53
	v_mul_f32_e32 v58, v50, v50
	v_max_f32_e32 v50, 0, v55
	v_mul_f32_e32 v55, v51, v51
	v_max_f32_e32 v51, 0, v56
	v_mul_f32_e32 v56, v52, v52
	v_max_f32_e32 v52, 0, v57
	v_mul_f32_e32 v54, v54, v54
	v_mul_f32_e32 v50, v50, v50
	v_mul_f32_e32 v51, v51, v51
	v_mul_f32_e32 v52, v52, v52
	v_mul_f32_e32 v53, v53, v53
	v_max_f32_e32 v42, 0, v42
	v_cvt_pk_bf16_f32 v50, v54, v50
	v_cvt_pk_bf16_f32 v51, v51, v52
	v_cvt_pk_bf16_f32 v52, v58, v55
	v_cvt_pk_bf16_f32 v53, v56, v53
	global_store_dwordx4 v[62:63], v[50:53], off offset:256
	s_nop 1
	v_max_f32_e32 v43, 0, v43
	v_mul_f32_e32 v53, v42, v42
	v_max_f32_e32 v42, 0, v47
	v_mul_f32_e32 v54, v42, v42
	v_mul_f32_e32 v55, v43, v43
	v_max_f32_e32 v42, 0, v48
	v_max_f32_e32 v43, 0, v44
	v_add_u32_e32 v50, 0x90, v140
	v_ashrrev_i32_e32 v51, 31, v50
	v_max_f32_e32 v46, 0, v46
	v_mul_f32_e32 v44, v42, v42
	v_mul_f32_e32 v48, v43, v43
	v_max_f32_e32 v42, 0, v49
	v_max_f32_e32 v43, 0, v45
	v_lshlrev_b64 v[50:51], 13, v[50:51]
	v_mul_f32_e32 v52, v46, v46
	v_mul_f32_e32 v45, v42, v42
	v_mul_f32_e32 v49, v43, v43
	v_lshl_add_u64 v[42:43], s[22:23], 0, v[50:51]
	v_max_f32_e32 v34, 0, v34
	v_max_f32_e32 v35, 0, v35
	v_max_f32_e32 v36, 0, v36
	v_lshl_add_u64 v[46:47], v[42:43], 0, v[122:123]
	v_cvt_pk_bf16_f32 v42, v52, v54
	v_cvt_pk_bf16_f32 v43, v44, v45
	v_cvt_pk_bf16_f32 v44, v53, v55
	v_cvt_pk_bf16_f32 v45, v48, v49
	global_store_dwordx4 v[46:47], v[42:45], off
	s_nop 1
	v_max_f32_e32 v38, 0, v38
	v_max_f32_e32 v37, 0, v37
	v_mul_f32_e32 v42, v34, v34
	v_max_f32_e32 v34, 0, v39
	v_mul_f32_e32 v39, v35, v35
	v_max_f32_e32 v35, 0, v40
	v_mul_f32_e32 v40, v36, v36
	v_max_f32_e32 v36, 0, v41
	v_mul_f32_e32 v38, v38, v38
	v_mul_f32_e32 v34, v34, v34
	v_mul_f32_e32 v35, v35, v35
	v_mul_f32_e32 v36, v36, v36
	v_mul_f32_e32 v37, v37, v37
	v_max_f32_e32 v26, 0, v26
	v_cvt_pk_bf16_f32 v34, v38, v34
	v_cvt_pk_bf16_f32 v35, v35, v36
	v_cvt_pk_bf16_f32 v36, v42, v39
	v_cvt_pk_bf16_f32 v37, v40, v37
	global_store_dwordx4 v[46:47], v[34:37], off offset:256
	s_nop 1
	v_max_f32_e32 v27, 0, v27
	v_mul_f32_e32 v37, v26, v26
	v_max_f32_e32 v26, 0, v31
	v_mul_f32_e32 v38, v26, v26
	v_mul_f32_e32 v39, v27, v27
	v_max_f32_e32 v26, 0, v32
	v_max_f32_e32 v27, 0, v28
	v_add_u32_e32 v34, 0xa0, v140
	v_ashrrev_i32_e32 v35, 31, v34
	v_max_f32_e32 v30, 0, v30
	v_mul_f32_e32 v28, v26, v26
	v_mul_f32_e32 v32, v27, v27
	v_max_f32_e32 v26, 0, v33
	v_max_f32_e32 v27, 0, v29
	v_lshlrev_b64 v[34:35], 13, v[34:35]
	v_mul_f32_e32 v36, v30, v30
	v_mul_f32_e32 v29, v26, v26
	v_mul_f32_e32 v33, v27, v27
	v_lshl_add_u64 v[26:27], s[22:23], 0, v[34:35]
	v_max_f32_e32 v18, 0, v18
	v_max_f32_e32 v19, 0, v19
	v_max_f32_e32 v20, 0, v20
	v_lshl_add_u64 v[30:31], v[26:27], 0, v[122:123]
	v_cvt_pk_bf16_f32 v26, v36, v38
	v_cvt_pk_bf16_f32 v27, v28, v29
	v_cvt_pk_bf16_f32 v28, v37, v39
	v_cvt_pk_bf16_f32 v29, v32, v33
	global_store_dwordx4 v[30:31], v[26:29], off
	s_nop 1
	v_max_f32_e32 v22, 0, v22
	v_max_f32_e32 v21, 0, v21
	v_mul_f32_e32 v26, v18, v18
	v_max_f32_e32 v18, 0, v23
	v_mul_f32_e32 v23, v19, v19
	v_max_f32_e32 v19, 0, v24
	v_mul_f32_e32 v24, v20, v20
	v_max_f32_e32 v20, 0, v25
	v_mul_f32_e32 v22, v22, v22
	v_mul_f32_e32 v18, v18, v18
	v_mul_f32_e32 v19, v19, v19
	v_mul_f32_e32 v20, v20, v20
	v_mul_f32_e32 v21, v21, v21
	v_max_f32_e32 v10, 0, v10
	v_cvt_pk_bf16_f32 v18, v22, v18
	v_cvt_pk_bf16_f32 v19, v19, v20
	v_cvt_pk_bf16_f32 v20, v26, v23
	v_cvt_pk_bf16_f32 v21, v24, v21
	global_store_dwordx4 v[30:31], v[18:21], off offset:256
	s_nop 1
	v_max_f32_e32 v11, 0, v11
	v_mul_f32_e32 v21, v10, v10
	v_max_f32_e32 v10, 0, v15
	v_mul_f32_e32 v22, v10, v10
	v_mul_f32_e32 v23, v11, v11
	v_max_f32_e32 v10, 0, v16
	v_max_f32_e32 v11, 0, v12
	v_add_u32_e32 v18, 0xb0, v140
	v_ashrrev_i32_e32 v19, 31, v18
	v_max_f32_e32 v14, 0, v14
	v_mul_f32_e32 v12, v10, v10
	v_mul_f32_e32 v16, v11, v11
	v_max_f32_e32 v10, 0, v17
	v_max_f32_e32 v11, 0, v13
	v_lshlrev_b64 v[18:19], 13, v[18:19]
	v_mul_f32_e32 v20, v14, v14
	v_mul_f32_e32 v13, v10, v10
	v_mul_f32_e32 v17, v11, v11
	v_lshl_add_u64 v[10:11], s[22:23], 0, v[18:19]
	v_max_f32_e32 v2, 0, v2
	v_max_f32_e32 v3, 0, v3
	v_max_f32_e32 v4, 0, v4
	v_lshl_add_u64 v[14:15], v[10:11], 0, v[122:123]
	v_cvt_pk_bf16_f32 v10, v20, v22
	v_cvt_pk_bf16_f32 v11, v12, v13
	v_cvt_pk_bf16_f32 v12, v21, v23
	v_cvt_pk_bf16_f32 v13, v16, v17
	global_store_dwordx4 v[14:15], v[10:13], off
	s_nop 1
	v_max_f32_e32 v6, 0, v6
	v_max_f32_e32 v5, 0, v5
	v_mul_f32_e32 v10, v2, v2
	v_max_f32_e32 v2, 0, v7
	v_mul_f32_e32 v7, v3, v3
	v_max_f32_e32 v3, 0, v8
	v_mul_f32_e32 v8, v4, v4
	v_max_f32_e32 v4, 0, v9
	v_mul_f32_e32 v6, v6, v6
	v_mul_f32_e32 v2, v2, v2
	v_mul_f32_e32 v3, v3, v3
	v_mul_f32_e32 v4, v4, v4
	v_mul_f32_e32 v5, v5, v5
	v_cvt_pk_bf16_f32 v2, v6, v2
	v_cvt_pk_bf16_f32 v3, v3, v4
	v_cvt_pk_bf16_f32 v4, v10, v7
	v_cvt_pk_bf16_f32 v5, v8, v5
	s_andn2_b64 vcc, exec, s[42:43]
	s_mov_b64 s[42:43], -1
	global_store_dwordx4 v[14:15], v[2:5], off offset:256
	s_nop 1
	s_cbranch_vccnz .LBB0_508
	s_andn2_b64 vcc, exec, s[6:7]
	s_cbranch_vccnz .LBB0_507
	s_barrier
	s_branch .LBB0_507

; DEVI void phase_prep(const Params& p, float* lds) {
;     ...
;         for (int i = first; i < ntile; i += gridDim.x) {
;             const int k0 = (i % tk) * 64, n0 = (i / tk) * 64;
;             __syncthreads();
; #pragma unroll
;             for (int e = 0; e < 2; ++e) {
;                 const int idx = tid + e * 512, kk = idx >> 4, n4 = (idx & 15) * 4, n = n0 + n4;
;                 f32x4 v = {0.f, 0.f, 0.f, 0.f};
;                 if (n < t.N) { v = *(const f32x4*)(t.src + (size_t)(k0 + kk) * t.src_ld + n); if (n < t.scale_cols) v = v * t.scale; if (t.kgain) v = v * t.kgain[k0 + kk]; }
;                 lds[kk * 65 + n4] = v[0]; lds[kk * 65 + n4 + 1] = v[1]; lds[kk * 65 + n4 + 2] = v[2]; lds[kk * 65 + n4 + 3] = v[3];
;             }
.LBB0_853:
	s_abs_i32 s1, s68
	s_mul_hi_u32 s28, s1, s69
	s_mul_i32 s29, s28, s49
	s_sub_i32 s1, s1, s29
	s_ashr_i32 s0, s68, 31
	s_add_i32 s29, s28, 1
	s_sub_i32 s38, s1, s49
	s_cmp_ge_u32 s1, s49
	s_cselect_b32 s28, s29, s28
	s_cselect_b32 s1, s38, s1
	s_add_i32 s29, s28, 1
	s_cmp_ge_u32 s1, s49
	s_cselect_b32 s1, s29, s28
	s_xor_b32 s1, s1, s0
	s_sub_i32 s38, s1, s0
	s_lshl_b32 s73, s38, 6
	v_or_b32_e32 v6, s73, v10
	v_cmp_le_i32_e32 vcc, s24, v6
	s_nop 0
	s_barrier
	s_and_saveexec_b64 s[0:1], vcc
	s_xor_b64 s[0:1], exec, s[0:1]
	s_cbranch_execz .LBB0_855
	ds_write2_b32 v17, v1, v1 offset1:1
	ds_write2_b32 v17, v1, v1 offset0:2 offset1:3
.LBB0_855:
	s_or_saveexec_b64 s[42:43], s[0:1]
	s_mul_i32 s74, s70, s38
	v_mov_b32_e32 v3, 0
	v_mov_b32_e32 v2, 0
	v_mov_b32_e32 v5, 0
	v_mov_b32_e32 v4, 0
	s_xor_b64 exec, exec, s[42:43]
	s_cbranch_execz .LBB0_852
	s_add_i32 s75, s74, s71
	v_add_u32_e32 v4, s75, v13
	v_mad_u64_u32 v[8:9], s[0:1], v4, s24, 0
	v_ashrrev_i32_e32 v5, 31, v4
	v_mov_b32_e32 v18, v9
	v_ashrrev_i32_e32 v7, 31, v6
	v_mad_u64_u32 v[18:19], s[0:1], v5, s24, v[18:19]
	v_lshl_add_u64 v[2:3], v[6:7], 2, s[6:7]
	v_mov_b32_e32 v9, v18
	v_lshl_add_u64 v[8:9], v[8:9], 2, v[2:3]
	global_load_dwordx4 v[18:21], v[8:9], off
	v_add_u32_e32 v60, s75, v14
	v_mad_u64_u32 v[62:63], s[76:77], v60, s24, 0
	v_ashrrev_i32_e32 v61, 31, v60
	v_mov_b32_e32 v64, v63
	v_mad_u64_u32 v[64:65], s[76:77], v61, s24, v[64:65]
	v_mov_b32_e32 v63, v64
	v_lshl_add_u64 v[62:63], v[62:63], 2, v[2:3]
	global_load_dwordx4 v[54:57], v[62:63], off
	v_cmp_gt_i32_e64 s[38:39], s46, v6
	s_andn2_b64 vcc, exec, s[40:41]
	s_cbranch_vccnz .Ltr_nogain
	v_lshl_add_u64 v[4:5], v[4:5], 2, s[16:17]
	global_load_dword v58, v[4:5], off
	v_lshl_add_u64 v[60:61], v[60:61], 2, s[16:17]
	global_load_dword v59, v[60:61], off
	s_waitcnt vmcnt(0)
	v_pk_mul_f32 v[8:9], s[18:19], v[20:21]
	v_pk_mul_f32 v[22:23], s[14:15], v[18:19]
	v_cndmask_b32_e64 v9, v21, v9, s[38:39]
	v_cndmask_b32_e64 v7, v19, v23, s[38:39]
	v_cndmask_b32_e64 v6, v18, v22, s[38:39]
	v_cndmask_b32_e64 v8, v20, v8, s[38:39]
	v_mul_f32_e32 v8, v8, v58
	v_mul_f32_e32 v9, v9, v58
	v_mul_f32_e32 v6, v6, v58
	v_mul_f32_e32 v7, v7, v58
	v_pk_mul_f32 v[2:3], s[18:19], v[56:57]
	v_pk_mul_f32 v[4:5], s[14:15], v[54:55]
	v_cndmask_b32_e64 v3, v57, v3, s[38:39]
	v_cndmask_b32_e64 v5, v55, v5, s[38:39]
	v_cndmask_b32_e64 v4, v54, v4, s[38:39]
	v_cndmask_b32_e64 v2, v56, v2, s[38:39]
	v_mul_f32_e32 v2, v2, v59
	v_mul_f32_e32 v3, v3, v59
	v_mul_f32_e32 v4, v4, v59
	v_mul_f32_e32 v5, v5, v59
	s_branch .Ltr_write
.Ltr_nogain:
	s_waitcnt vmcnt(0)
	v_pk_mul_f32 v[8:9], s[18:19], v[20:21]
	v_pk_mul_f32 v[22:23], s[14:15], v[18:19]
	v_cndmask_b32_e64 v9, v21, v9, s[38:39]
	v_cndmask_b32_e64 v7, v19, v23, s[38:39]
	v_cndmask_b32_e64 v6, v18, v22, s[38:39]
	v_cndmask_b32_e64 v8, v20, v8, s[38:39]
	v_pk_mul_f32 v[2:3], s[18:19], v[56:57]
	v_pk_mul_f32 v[4:5], s[14:15], v[54:55]
	v_cndmask_b32_e64 v3, v57, v3, s[38:39]
	v_cndmask_b32_e64 v5, v55, v5, s[38:39]
	v_cndmask_b32_e64 v4, v54, v4, s[38:39]
	v_cndmask_b32_e64 v2, v56, v2, s[38:39]
.Ltr_write:
	ds_write2_b32 v17, v6, v7 offset1:1
	ds_write2_b32 v17, v8, v9 offset0:2 offset1:3
	s_branch .LBB0_852
